# v21 plus GLA sample-item gate logits: 16 weight rows and low-rank input requested together instead of nine dependent round trips
# baseline (speedup 1.0000x reference)
; __device__ __forceinline__ float bf2f(bf16_t b) { return __uint_as_float(((unsigned)b) << 16); }
; __device__ __forceinline__ float logsigmoidf_(float x) { return fminf(x, 0.f) - __logf(1.0f + __expf(-fabsf(x))); }
; template <bool RET>
; __device__ __forceinline__ void recur_sample_item(ParamsK p, int l, int item, LAS unsigned char* lds) {
;     ...
;     if (tid < 128) {
;         qs[tid] = bf2f(proj[row * NIN + (RET ? OFF_RQ : OFF_GQ) + h * 128 + tid]);
;         ks[tid] = bf2f(proj[row * NIN + (RET ? OFF_RK : OFF_GK) + h * 128 + tid]);
;         float dec;
;         if (RET) dec = 1.0f - exp2f(-5.0f - (float)h);
;         else { float lo = p->in[20][l * 512 + h * 128 + tid];
; #pragma unroll
;             for (int rr = 0; rr < 16; ++rr) lo += bf2f(proj[row * NIN + OFF_GLR + rr]) * p->in[19][((size_t)l * 16 + rr) * 512 + h * 128 + tid];
;             dec = __expf(logsigmoidf_(lo) * 0.0625f); }
;         ds[tid] = dec;
.LBB0_681:
	s_and_b64 vcc, exec, s[4:5]
	s_cbranch_vccz .LBB0_656
	s_ashr_i32 s4, s24, 31
	s_lshr_b32 s4, s4, 30
	s_add_i32 s20, s24, s4
	s_ashr_i32 s21, s20, 2
	v_mov_b32_e32 v6, v176
	s_add_i32 s14, s21, 0x2000
	s_ashr_i32 s15, s14, 31
	v_cmp_lt_i32_e32 vcc, s35, v6
	s_mul_hi_i32 s17, s14, 0x7200
	s_mul_i32 s16, s14, 0x7200
	s_and_saveexec_b64 s[4:5], vcc
	s_xor_b64 s[4:5], exec, s[4:5]
	s_or_saveexec_b64 s[18:19], s[4:5]
	s_and_b32 s4, s20, -4
	s_sub_i32 s20, s24, s4
	v_mov_b64_e32 v[12:13], s[16:17]
	v_ashrrev_i32_e32 v7, 31, v6
	v_lshl_add_u32 v50, v6, 2, 0
	s_xor_b64 exec, exec, s[18:19]
	s_cbranch_execz .LBB0_684
	s_lshl_b32 s22, s20, 7
	s_ashr_i32 s23, s22, 31
	s_add_u32 s4, s12, s16
	s_addc_u32 s5, s13, s17
	s_lshl_b64 s[24:25], s[22:23], 1
	s_add_u32 s24, s4, s24
	s_addc_u32 s25, s5, s25
	v_lshl_add_u64 v[2:3], v[6:7], 1, s[24:25]
	global_load_ushort v0, v[2:3], off offset:2048
	s_load_dwordx4 s[24:27], s[0:1], 0x98
	global_load_ushort v2, v[2:3], off offset:3072
	s_add_i32 s28, s22, s30
	s_lshl_b64 s[22:23], s[22:23], 2
	global_load_dwordx4 v[8:11], v182, s[4:5]
	s_waitcnt lgkmcnt(0)
	s_add_u32 s22, s24, s22
	s_addc_u32 s23, s25, s23
	s_waitcnt vmcnt(2)
	v_lshlrev_b32_e32 v0, 16, v0
	s_waitcnt vmcnt(1)
	v_lshlrev_b32_e32 v2, 16, v2
	ds_write2st64_b32 v50, v0, v2 offset1:2
	v_add_u32_e32 v2, s28, v6
	v_ashrrev_i32_e32 v3, 31, v2
	v_lshl_add_u64 v[2:3], v[2:3], 2, s[26:27]
	global_load_dword v0, v[2:3], off
	v_lshl_add_u64 v[2:3], v[6:7], 2, s[22:23]
	v_lshl_add_u64 v[2:3], s[8:9], 2, v[2:3]
	global_load_dwordx4 v[116:119], v182, s[4:5] offset:16
	global_load_dword v100, v[2:3], off
	global_load_dword v101, v[2:3], off offset:2048
	s_mov_b64 s[22:23], 0x1000
	v_lshl_add_u64 v[120:121], v[2:3], 0, s[22:23]
	global_load_dword v102, v[120:121], off
	global_load_dword v103, v[120:121], off offset:2048
	s_mov_b64 s[22:23], 0x2000
	v_lshl_add_u64 v[122:123], v[2:3], 0, s[22:23]
	global_load_dword v104, v[122:123], off
	global_load_dword v105, v[122:123], off offset:2048
	s_mov_b64 s[22:23], 0x3000
	v_lshl_add_u64 v[120:121], v[2:3], 0, s[22:23]
	global_load_dword v106, v[120:121], off
	global_load_dword v107, v[120:121], off offset:2048
	s_mov_b64 s[22:23], 0x4000
	v_lshl_add_u64 v[122:123], v[2:3], 0, s[22:23]
	global_load_dword v108, v[122:123], off
	global_load_dword v109, v[122:123], off offset:2048
	s_mov_b64 s[22:23], 0x5000
	v_lshl_add_u64 v[120:121], v[2:3], 0, s[22:23]
	global_load_dword v110, v[120:121], off
	global_load_dword v111, v[120:121], off offset:2048
	s_mov_b64 s[22:23], 0x6000
	v_lshl_add_u64 v[122:123], v[2:3], 0, s[22:23]
	global_load_dword v112, v[122:123], off
	global_load_dword v113, v[122:123], off offset:2048
	s_mov_b64 s[22:23], 0x7000
	v_lshl_add_u64 v[120:121], v[2:3], 0, s[22:23]
	global_load_dword v114, v[120:121], off
	global_load_dword v115, v[120:121], off offset:2048
	s_waitcnt vmcnt(0)
	v_lshlrev_b32_e32 v4, 16, v8
	v_fmac_f32_e32 v0, v100, v4
	v_and_b32_e32 v4, 0xffff0000, v8
	v_fmac_f32_e32 v0, v101, v4
	v_lshlrev_b32_e32 v4, 16, v9
	v_fmac_f32_e32 v0, v102, v4
	v_and_b32_e32 v4, 0xffff0000, v9
	v_fmac_f32_e32 v0, v103, v4
	v_lshlrev_b32_e32 v4, 16, v10
	v_fmac_f32_e32 v0, v104, v4
	v_and_b32_e32 v4, 0xffff0000, v10
	v_fmac_f32_e32 v0, v105, v4
	v_lshlrev_b32_e32 v4, 16, v11
	v_fmac_f32_e32 v0, v106, v4
	v_and_b32_e32 v4, 0xffff0000, v11
	v_fmac_f32_e32 v0, v107, v4
	v_lshlrev_b32_e32 v4, 16, v116
	v_fmac_f32_e32 v0, v108, v4
	v_and_b32_e32 v4, 0xffff0000, v116
	v_fmac_f32_e32 v0, v109, v4
	v_lshlrev_b32_e32 v4, 16, v117
	v_fmac_f32_e32 v0, v110, v4
	v_and_b32_e32 v4, 0xffff0000, v117
	v_fmac_f32_e32 v0, v111, v4
	v_lshlrev_b32_e32 v4, 16, v118
	v_fmac_f32_e32 v0, v112, v4
	v_and_b32_e32 v4, 0xffff0000, v118
	v_fmac_f32_e32 v0, v113, v4
	v_lshlrev_b32_e32 v4, 16, v119
	v_fmac_f32_e32 v0, v114, v4
	v_and_b32_e32 v4, 0xffff0000, v119
	v_fmac_f32_e32 v0, v115, v4
	v_mov_b64_e32 v[12:13], s[16:17]
	v_min_f32_e32 v2, 0, v0
	v_mul_f32_e64 v0, |v0|, s72
	v_exp_f32_e32 v0, v0
	s_nop 0
	v_add_f32_e32 v0, 1.0, v0
	v_cmp_gt_f32_e32 vcc, s61, v0
	s_nop 1
	v_cndmask_b32_e64 v3, 0, 32, vcc
	v_ldexp_f32 v0, v0, v3
	v_log_f32_e32 v0, v0
	s_nop 0
	v_mul_f32_e32 v3, 0x3f317217, v0
	v_fma_f32 v3, v0, s56, -v3
	v_fmac_f32_e32 v3, 0x3377d1cf, v0
	v_fmac_f32_e32 v3, 0x3f317217, v0
	v_cmp_lt_f32_e64 s[4:5], |v0|, s96
	s_nop 1
	v_cndmask_b32_e64 v0, v0, v3, s[4:5]
	v_cndmask_b32_e32 v3, 0, v186, vcc
	v_sub_f32_e32 v0, v0, v3
	v_sub_f32_e32 v0, v2, v0
	v_mul_f32_e32 v0, 0x3d800000, v0
	v_mul_f32_e32 v0, 0x3fb8aa3b, v0
	v_exp_f32_e32 v0, v0
	ds_write_b32 v50, v0 offset:1024
